# LayerNorm loops: both rows of an iteration fetch their shift/scale (and the shared gain/bias) in one batch
# speedup vs baseline: 1.0182x; 1.0028x over previous
; DI void ln_rows(const Params& p, const float* g, const float* bb, int nrows, int mod_layer, int sh_chunk, bool write_act) {
;     ...
;       const float* m = (const float*)(p.ws + O_MOD) + (size_t)mod_layer * 17 * 6144 + rowb(row) * 6144 + sh_chunk * 1024;
; #pragma unroll
;       for (int i = 0; i < 4; ++i) {
;         int col = (i * 64 + lane) * 4;
;         float4 v = rr ? vb[i] : va[i];
;         float4 gg = *(const float4*)(g + col);
;         float4 bv = *(const float4*)(bb + col);
;         float4 y;
;         y.x = v.x * rstd * gg.x + bv.x; y.y = v.y * rstd * gg.y + bv.y;
;         y.z = v.z * rstd * gg.z + bv.z; y.w = v.w * rstd * gg.w + bv.w;
;         if (!write_act) *(float4*)(dst + col) = y;
;         if (write_act) {
;           float4 sh = *(const float4*)(m + col);
;           float4 sc = *(const float4*)(m + 1024 + col);
;           uint2 o;
;           o.x = pack2(y.x * (1.f + sc.x) + sh.x, y.y * (1.f + sc.y) + sh.y);
;           o.y = pack2(y.z * (1.f + sc.z) + sh.z, y.w * (1.f + sc.w) + sh.w);
;           *(uint2*)(act + (size_t)row * AP + col) = o;
;         }
.LBB0_809:
	s_or_b64 exec, exec, s[2:3]
	v_min_i32_e32 v14, 0x10000, v81
	v_ashrrev_i32_e32 v14, 12, v14
	v_mul_i32_i24_e32 v14, 0x1800, v14
	v_ashrrev_i32_e32 v15, 31, v14
	v_lshl_add_u64 v[14:15], v[14:15], 2, s[10:11]
	s_mov_b64 s[2:3], 0x1000
	v_lshl_add_u64 v[16:17], v[14:15], 0, s[2:3]
	v_pk_mul_f32 v[18:19], v[56:57], v[20:21] op_sel_hi:[1,0]
	v_lshl_add_u64 v[14:15], v[14:15], 0, v[0:1]
	v_lshl_add_u64 v[56:57], v[16:17], 0, v[0:1]
	v_pk_mul_f32 v[60:61], v[58:59], v[20:21] op_sel_hi:[1,0]
	s_waitcnt vmcnt(10)
	v_mov_b64_e32 v[22:23], v[90:91]
	v_mov_b64_e32 v[24:25], v[92:93]
	v_mov_b64_e32 v[26:27], v[106:107]
	v_mov_b64_e32 v[28:29], v[108:109]
	v_mov_b64_e32 v[30:31], v[170:171]
	v_mov_b64_e32 v[32:33], v[172:173]
	s_nop 0
	v_mov_b64_e32 v[56:57], v[174:175]
	v_mov_b64_e32 v[58:59], v[176:177]
	s_mov_b32 s2, 0x50cc000
	v_mov_b32_e32 v51, v1
	v_mov_b32_e32 v53, v1
	v_mov_b32_e32 v55, v1
	v_pk_fma_f32 v[18:19], v[18:19], v[22:23], v[26:27]
	v_pk_add_f32 v[22:23], v[56:57], 1.0 op_sel_hi:[1,0]
	v_pk_mul_f32 v[26:27], v[10:11], v[20:21] op_sel_hi:[1,0]
	v_pk_fma_f32 v[18:19], v[18:19], v[22:23], v[30:31]
	v_pk_mul_f32 v[56:57], v[12:13], v[20:21] op_sel_hi:[1,0]
	v_cvt_pk_bf16_f32 v22, v18, v19
	v_pk_fma_f32 v[18:19], v[60:61], v[24:25], v[28:29]
	v_pk_add_f32 v[24:25], v[58:59], 1.0 op_sel_hi:[1,0]
	v_lshl_add_u64 v[30:31], v[16:17], 0, v[50:51]
	v_pk_fma_f32 v[18:19], v[18:19], v[24:25], v[32:33]
	s_nop 0
	v_cvt_pk_bf16_f32 v23, v18, v19
	v_lshl_add_u64 v[18:19], s[84:85], 0, v[48:49]
	v_add_co_u32_e32 v18, vcc, s2, v18
	s_nop 1
	v_addc_co_u32_e32 v19, vcc, 0, v19, vcc
	global_store_dwordx2 v[18:19], v[22:23], off offset:256
	s_waitcnt vmcnt(9)
	v_mov_b64_e32 v[10:11], v[94:95]
	v_mov_b64_e32 v[12:13], v[96:97]
	s_nop 0
	v_mov_b64_e32 v[22:23], v[110:111]
	v_mov_b64_e32 v[24:25], v[112:113]
	v_pk_fma_f32 v[10:11], v[26:27], v[10:11], v[22:23]
	v_mov_b64_e32 v[26:27], v[178:179]
	v_mov_b64_e32 v[28:29], v[180:181]
	s_nop 0
	v_mov_b64_e32 v[30:31], v[186:187]
	v_mov_b64_e32 v[32:33], v[188:189]
	v_pk_fma_f32 v[12:13], v[56:57], v[12:13], v[24:25]
	v_pk_add_f32 v[22:23], v[30:31], 1.0 op_sel_hi:[1,0]
	s_nop 0
	v_pk_fma_f32 v[10:11], v[10:11], v[22:23], v[26:27]
	v_pk_add_f32 v[22:23], v[32:33], 1.0 op_sel_hi:[1,0]
	v_cvt_pk_bf16_f32 v10, v10, v11
	v_pk_fma_f32 v[12:13], v[12:13], v[22:23], v[28:29]
	v_pk_mul_f32 v[22:23], v[6:7], v[20:21] op_sel_hi:[1,0]
	v_cvt_pk_bf16_f32 v11, v12, v13
	global_store_dwordx2 v[18:19], v[10:11], off offset:768
	v_pk_mul_f32 v[30:31], v[8:9], v[20:21] op_sel_hi:[1,0]
	s_waitcnt vmcnt(8)
	v_mov_b64_e32 v[6:7], v[98:99]
	v_mov_b64_e32 v[8:9], v[100:101]
	v_mov_b64_e32 v[10:11], v[114:115]
	v_mov_b64_e32 v[12:13], v[116:117]
	v_lshl_add_u64 v[26:27], v[16:17], 0, v[52:53]
	v_lshl_add_u64 v[16:17], v[16:17], 0, v[54:55]
	v_pk_fma_f32 v[6:7], v[22:23], v[6:7], v[10:11]
	v_mov_b64_e32 v[22:23], v[190:191]
	v_mov_b64_e32 v[24:25], v[192:193]
	s_nop 0
	v_mov_b64_e32 v[26:27], v[194:195]
	v_mov_b64_e32 v[28:29], v[196:197]
	v_pk_fma_f32 v[8:9], v[30:31], v[8:9], v[12:13]
	v_pk_add_f32 v[10:11], v[26:27], 1.0 op_sel_hi:[1,0]
	s_nop 0
	v_pk_fma_f32 v[6:7], v[6:7], v[10:11], v[22:23]
	v_pk_add_f32 v[10:11], v[28:29], 1.0 op_sel_hi:[1,0]
	v_cvt_pk_bf16_f32 v6, v6, v7
	v_pk_fma_f32 v[8:9], v[8:9], v[10:11], v[24:25]
	v_pk_mul_f32 v[10:11], v[2:3], v[20:21] op_sel_hi:[1,0]
	v_cvt_pk_bf16_f32 v7, v8, v9
	global_store_dwordx2 v[18:19], v[6:7], off offset:1280
	v_pk_mul_f32 v[20:21], v[4:5], v[20:21] op_sel_hi:[1,0]
	s_waitcnt vmcnt(7)
	v_mov_b64_e32 v[2:3], v[102:103]
	v_mov_b64_e32 v[4:5], v[104:105]
	v_mov_b64_e32 v[6:7], v[118:119]
	v_mov_b64_e32 v[8:9], v[120:121]
	v_pk_fma_f32 v[2:3], v[10:11], v[2:3], v[6:7]
	v_mov_b64_e32 v[10:11], v[198:199]
	v_mov_b64_e32 v[12:13], v[200:201]
	s_nop 0
	v_mov_b64_e32 v[14:15], v[202:203]
	v_mov_b64_e32 v[16:17], v[204:205]
	v_pk_fma_f32 v[4:5], v[20:21], v[4:5], v[8:9]
	v_pk_add_f32 v[6:7], v[14:15], 1.0 op_sel_hi:[1,0]
	s_nop 0
	v_pk_fma_f32 v[2:3], v[2:3], v[6:7], v[10:11]
	v_pk_add_f32 v[6:7], v[16:17], 1.0 op_sel_hi:[1,0]
	v_cvt_pk_bf16_f32 v2, v2, v3
	v_pk_fma_f32 v[4:5], v[4:5], v[6:7], v[12:13]
	s_nop 0
	v_cvt_pk_bf16_f32 v3, v4, v5
	global_store_dwordx2 v[18:19], v[2:3], off offset:1792

; DI void ln_rows(const Params& p, const float* g, const float* bb, int nrows, int mod_layer, int sh_chunk, bool write_act) {
;     ...
;       const float* m = (const float*)(p.ws + O_MOD) + (size_t)mod_layer * 17 * 6144 + rowb(row) * 6144 + sh_chunk * 1024;
; #pragma unroll
;       for (int i = 0; i < 4; ++i) {
;         int col = (i * 64 + lane) * 4;
;         float4 v = rr ? vb[i] : va[i];
;         float4 gg = *(const float4*)(g + col);
;         float4 bv = *(const float4*)(bb + col);
;         float4 y;
;         y.x = v.x * rstd * gg.x + bv.x; y.y = v.y * rstd * gg.y + bv.y;
;         y.z = v.z * rstd * gg.z + bv.z; y.w = v.w * rstd * gg.w + bv.w;
;         if (!write_act) *(float4*)(dst + col) = y;
;         if (write_act) {
;           float4 sh = *(const float4*)(m + col);
;           float4 sc = *(const float4*)(m + 1024 + col);
;           uint2 o;
;           o.x = pack2(y.x * (1.f + sc.x) + sh.x, y.y * (1.f + sc.y) + sh.y);
;           o.y = pack2(y.z * (1.f + sc.z) + sh.z, y.w * (1.f + sc.w) + sh.w);
;           *(uint2*)(act + (size_t)row * AP + col) = o;
;         }
.LBB0_821:
	s_or_b64 exec, exec, s[16:17]
	v_min_i32_e32 v15, 0x10000, v80
	v_ashrrev_i32_e32 v15, 12, v15
	v_mul_i32_i24_e32 v16, 0x1800, v15
	v_ashrrev_i32_e32 v17, 31, v16
	v_lshl_add_u64 v[16:17], v[16:17], 2, s[10:11]
	s_mov_b64 s[16:17], 0x1000
	v_lshl_add_u64 v[22:23], v[16:17], 0, s[16:17]
	v_lshl_add_u64 v[16:17], v[16:17], 0, v[0:1]
	v_lshl_add_u64 v[86:87], v[22:23], 0, v[0:1]
	v_pk_mul_f32 v[24:25], v[68:69], v[26:27] op_sel_hi:[1,0]
	v_pk_mul_f32 v[72:73], v[70:71], v[26:27] op_sel_hi:[1,0]
	v_mov_b64_e32 v[154:155], v[86:87]
	global_load_dwordx4 v[90:93], v[36:37], off
	global_load_dwordx4 v[106:109], v[38:39], off
	global_load_dwordx4 v[122:125], v[16:17], off
	global_load_dwordx4 v[138:141], v[154:155], off
	global_load_dwordx4 v[94:97], v[36:37], off offset:1024
	global_load_dwordx4 v[110:113], v[38:39], off offset:1024
	global_load_dwordx4 v[126:129], v[16:17], off offset:1024
	global_load_dwordx4 v[142:145], v[154:155], off offset:1024
	global_load_dwordx4 v[98:101], v[36:37], off offset:2048
	global_load_dwordx4 v[114:117], v[38:39], off offset:2048
	global_load_dwordx4 v[130:133], v[16:17], off offset:2048
	global_load_dwordx4 v[146:149], v[154:155], off offset:2048
	global_load_dwordx4 v[102:105], v[36:37], off offset:3072
	global_load_dwordx4 v[118:121], v[38:39], off offset:3072
	global_load_dwordx4 v[134:137], v[16:17], off offset:3072
	global_load_dwordx4 v[150:153], v[154:155], off offset:3072
	v_min_i32_e32 v166, 0x10000, v81
	v_ashrrev_i32_e32 v166, 12, v166
	v_mul_i32_i24_e32 v166, 0x1800, v166
	v_ashrrev_i32_e32 v167, 31, v166
	v_lshl_add_u64 v[166:167], v[166:167], 2, s[10:11]
	v_lshl_add_u64 v[166:167], v[166:167], 0, v[0:1]
	s_mov_b64 s[98:99], 0x1000
	v_lshl_add_u64 v[168:169], v[166:167], 0, s[98:99]
	global_load_dwordx4 v[170:173], v[166:167], off
	global_load_dwordx4 v[174:177], v[168:169], off
	global_load_dwordx4 v[178:181], v[166:167], off offset:1024
	global_load_dwordx4 v[186:189], v[168:169], off offset:1024
	global_load_dwordx4 v[190:193], v[166:167], off offset:2048
	global_load_dwordx4 v[194:197], v[168:169], off offset:2048
	global_load_dwordx4 v[198:201], v[166:167], off offset:3072
	global_load_dwordx4 v[202:205], v[168:169], off offset:3072
	s_waitcnt vmcnt(20)
	v_mov_b64_e32 v[30:31], v[90:91]
	v_mov_b64_e32 v[32:33], v[92:93]
	v_mov_b64_e32 v[68:69], v[106:107]
	v_mov_b64_e32 v[70:71], v[108:109]
	v_mov_b64_e32 v[82:83], v[122:123]
	v_mov_b64_e32 v[84:85], v[124:125]
	s_nop 0
	v_mov_b64_e32 v[86:87], v[138:139]
	v_mov_b64_e32 v[88:89], v[140:141]
	s_mov_b32 s16, 0x50cc000
	v_mov_b32_e32 v51, v1
	v_mov_b32_e32 v53, v1
	v_mov_b32_e32 v55, v1
	v_pk_fma_f32 v[24:25], v[24:25], v[30:31], v[68:69]
	v_pk_add_f32 v[30:31], v[86:87], 1.0 op_sel_hi:[1,0]
	v_pk_mul_f32 v[68:69], v[64:65], v[26:27] op_sel_hi:[1,0]
	v_pk_fma_f32 v[24:25], v[24:25], v[30:31], v[82:83]
	v_lshl_add_u64 v[82:83], v[22:23], 0, v[50:51]
	v_cvt_pk_bf16_f32 v30, v24, v25
	v_pk_fma_f32 v[24:25], v[72:73], v[32:33], v[70:71]
	v_pk_add_f32 v[32:33], v[88:89], 1.0 op_sel_hi:[1,0]
	v_pk_mul_f32 v[72:73], v[66:67], v[26:27] op_sel_hi:[1,0]
	v_pk_fma_f32 v[24:25], v[24:25], v[32:33], v[84:85]
	s_nop 0
	v_cvt_pk_bf16_f32 v31, v24, v25
	v_lshl_add_u64 v[24:25], s[84:85], 0, v[42:43]
	v_add_co_u32_e32 v24, vcc, s16, v24
	s_nop 1
	v_addc_co_u32_e32 v25, vcc, 0, v25, vcc
	global_store_dwordx2 v[24:25], v[30:31], off offset:256
	s_waitcnt vmcnt(17)
	v_mov_b64_e32 v[30:31], v[94:95]
	v_mov_b64_e32 v[32:33], v[96:97]
	s_nop 0
	v_mov_b64_e32 v[64:65], v[110:111]
	v_mov_b64_e32 v[66:67], v[112:113]
	v_pk_fma_f32 v[30:31], v[68:69], v[30:31], v[64:65]
	v_mov_b64_e32 v[68:69], v[126:127]
	v_mov_b64_e32 v[70:71], v[128:129]
	s_nop 0
	v_mov_b64_e32 v[82:83], v[142:143]
	v_mov_b64_e32 v[84:85], v[144:145]
	v_pk_fma_f32 v[32:33], v[72:73], v[32:33], v[66:67]
	v_pk_add_f32 v[64:65], v[82:83], 1.0 op_sel_hi:[1,0]
	s_nop 0
	v_pk_fma_f32 v[30:31], v[30:31], v[64:65], v[68:69]
	v_pk_add_f32 v[64:65], v[84:85], 1.0 op_sel_hi:[1,0]
	v_cvt_pk_bf16_f32 v30, v30, v31
	v_pk_fma_f32 v[32:33], v[32:33], v[64:65], v[70:71]
	v_lshl_add_u64 v[70:71], v[22:23], 0, v[52:53]
	v_cvt_pk_bf16_f32 v31, v32, v33
	global_store_dwordx2 v[24:25], v[30:31], off offset:768
	v_pk_mul_f32 v[32:33], v[28:29], v[26:27] op_sel_hi:[1,0]
	v_pk_mul_f32 v[82:83], v[62:63], v[26:27] op_sel_hi:[1,0]
	s_waitcnt vmcnt(14)
	v_mov_b64_e32 v[28:29], v[98:99]
	v_mov_b64_e32 v[30:31], v[100:101]
	v_mov_b64_e32 v[62:63], v[114:115]
	v_mov_b64_e32 v[64:65], v[116:117]
	v_mov_b64_e32 v[66:67], v[130:131]
	v_mov_b64_e32 v[68:69], v[132:133]
	s_nop 0
	v_mov_b64_e32 v[70:71], v[146:147]
	v_mov_b64_e32 v[72:73], v[148:149]
	v_lshl_add_u64 v[22:23], v[22:23], 0, v[54:55]
	v_pk_fma_f32 v[28:29], v[32:33], v[28:29], v[62:63]
	v_pk_add_f32 v[32:33], v[70:71], 1.0 op_sel_hi:[1,0]
	v_pk_fma_f32 v[30:31], v[82:83], v[30:31], v[64:65]
	v_pk_fma_f32 v[28:29], v[28:29], v[32:33], v[66:67]
	v_pk_add_f32 v[32:33], v[72:73], 1.0 op_sel_hi:[1,0]
	v_cvt_pk_bf16_f32 v28, v28, v29
	v_pk_fma_f32 v[30:31], v[30:31], v[32:33], v[68:69]
	v_pk_mul_f32 v[62:63], v[20:21], v[26:27] op_sel_hi:[1,0]
	v_cvt_pk_bf16_f32 v29, v30, v31
	global_store_dwordx2 v[24:25], v[28:29], off offset:1280
	v_pk_mul_f32 v[30:31], v[18:19], v[26:27] op_sel_hi:[1,0]
	s_waitcnt vmcnt(11)
	v_mov_b64_e32 v[18:19], v[102:103]
	v_mov_b64_e32 v[20:21], v[104:105]
	v_mov_b64_e32 v[26:27], v[118:119]
	v_mov_b64_e32 v[28:29], v[120:121]
	v_pk_fma_f32 v[26:27], v[30:31], v[18:19], v[26:27]
	v_mov_b64_e32 v[16:17], v[134:135]
	v_mov_b64_e32 v[18:19], v[136:137]
	s_nop 0
	v_mov_b64_e32 v[30:31], v[150:151]
	v_mov_b64_e32 v[32:33], v[152:153]
	v_pk_fma_f32 v[20:21], v[62:63], v[20:21], v[28:29]
	v_pk_add_f32 v[22:23], v[30:31], 1.0 op_sel_hi:[1,0]
	s_nop 0
	v_pk_fma_f32 v[16:17], v[26:27], v[22:23], v[16:17]
	v_pk_add_f32 v[22:23], v[32:33], 1.0 op_sel_hi:[1,0]
	v_cvt_pk_bf16_f32 v16, v16, v17
	v_pk_fma_f32 v[18:19], v[20:21], v[22:23], v[18:19]
	s_nop 0
	v_cvt_pk_bf16_f32 v17, v18, v19
	global_store_dwordx2 v[24:25], v[16:17], off offset:1792
	s_and_saveexec_b64 s[16:17], s[2:3]
	s_cbranch_execz .LBB0_810
	v_mul_f32_e32 v15, 0x4b800000, v14
	v_cndmask_b32_e64 v14, v14, v15, s[4:5]
	v_rsq_f32_e32 v14, v14
	s_nop 0
	v_mul_f32_e32 v15, 0x45800000, v14
	v_cndmask_b32_e64 v20, v14, v15, s[4:5]
	s_and_saveexec_b64 s[2:3], s[0:1]
	s_cbranch_execz .LBB0_809
	v_lshl_add_u64 v[14:15], s[84:85], 0, v[46:47]
	v_add_co_u32_e32 v14, vcc, 0x3e28c000, v14
	v_mov_b32_e32 v61, v20
	s_nop 0
	v_addc_co_u32_e32 v15, vcc, 0, v15, vcc
	global_store_dwordx2 v[14:15], v[60:61], off offset:256
	s_branch .LBB0_809

; DI void ln_rows(const Params& p, const float* g, const float* bb, int nrows, int mod_layer, int sh_chunk, bool write_act) {
;     ...
;       const float* m = (const float*)(p.ws + O_MOD) + (size_t)mod_layer * 17 * 6144 + rowb(row) * 6144 + sh_chunk * 1024;
; #pragma unroll
;       for (int i = 0; i < 4; ++i) {
;         int col = (i * 64 + lane) * 4;
;         float4 v = rr ? vb[i] : va[i];
;         float4 gg = *(const float4*)(g + col);
;         float4 bv = *(const float4*)(bb + col);
;         float4 y;
;         y.x = v.x * rstd * gg.x + bv.x; y.y = v.y * rstd * gg.y + bv.y;
;         y.z = v.z * rstd * gg.z + bv.z; y.w = v.w * rstd * gg.w + bv.w;
;         if (!write_act) *(float4*)(dst + col) = y;
;         if (write_act) {
;           float4 sh = *(const float4*)(m + col);
;           float4 sc = *(const float4*)(m + 1024 + col);
.LBB0_881:
	s_or_b64 exec, exec, s[4:5]
	global_load_dwordx4 v[90:93], v[44:45], off
	global_load_dwordx4 v[106:109], v[46:47], off
	global_load_dwordx4 v[94:97], v[44:45], off offset:1024
	global_load_dwordx4 v[110:113], v[46:47], off offset:1024
	global_load_dwordx4 v[98:101], v[44:45], off offset:2048
	global_load_dwordx4 v[114:117], v[46:47], off offset:2048
	global_load_dwordx4 v[102:105], v[44:45], off offset:3072
	global_load_dwordx4 v[118:121], v[46:47], off offset:3072
	s_and_b64 vcc, exec, s[74:75]
	s_cbranch_vccnz .Lln2_nomod_r0
	v_min_i32_e32 v156, 0x10000, v82
	v_ashrrev_i32_e32 v156, 12, v156
	v_mul_i32_i24_e32 v156, 0x1800, v156
	v_ashrrev_i32_e32 v157, 31, v156
	v_lshl_add_u64 v[156:157], v[156:157], 2, s[10:11]
	v_lshl_add_u64 v[156:157], v[156:157], 0, v[0:1]
	s_mov_b64 s[98:99], 0x1000
	v_lshl_add_u64 v[158:159], v[156:157], 0, s[98:99]
	global_load_dwordx4 v[122:125], v[156:157], off
	global_load_dwordx4 v[138:141], v[158:159], off
	global_load_dwordx4 v[126:129], v[156:157], off offset:1024
	global_load_dwordx4 v[142:145], v[158:159], off offset:1024
	global_load_dwordx4 v[130:133], v[156:157], off offset:2048
	global_load_dwordx4 v[146:149], v[158:159], off offset:2048
	global_load_dwordx4 v[134:137], v[156:157], off offset:3072
	global_load_dwordx4 v[150:153], v[158:159], off offset:3072
	v_min_i32_e32 v166, 0x10000, v83
	v_ashrrev_i32_e32 v166, 12, v166
	v_mul_i32_i24_e32 v166, 0x1800, v166
	v_ashrrev_i32_e32 v167, 31, v166
	v_lshl_add_u64 v[166:167], v[166:167], 2, s[10:11]
	v_lshl_add_u64 v[166:167], v[166:167], 0, v[0:1]
	v_lshl_add_u64 v[168:169], v[166:167], 0, s[98:99]
	global_load_dwordx4 v[170:173], v[166:167], off
	global_load_dwordx4 v[174:177], v[168:169], off
	global_load_dwordx4 v[178:181], v[166:167], off offset:1024
	global_load_dwordx4 v[186:189], v[168:169], off offset:1024
	global_load_dwordx4 v[190:193], v[166:167], off offset:2048
	global_load_dwordx4 v[194:197], v[168:169], off offset:2048
	global_load_dwordx4 v[198:201], v[166:167], off offset:3072
	global_load_dwordx4 v[202:205], v[168:169], off offset:3072

; DI void ln_rows(const Params& p, const float* g, const float* bb, int nrows, int mod_layer, int sh_chunk, bool write_act) {
;     ...
;         if (write_act) {
;           float4 sh = *(const float4*)(m + col);
;           float4 sc = *(const float4*)(m + 1024 + col);
;           uint2 o;
;           o.x = pack2(y.x * (1.f + sc.x) + sh.x, y.y * (1.f + sc.y) + sh.y);
;           o.y = pack2(y.z * (1.f + sc.z) + sh.z, y.w * (1.f + sc.w) + sh.w);
;           *(uint2*)(act + (size_t)row * AP + col) = o;
;         }
.LBB0_883:
	v_min_i32_e32 v15, 0x10000, v82
	v_ashrrev_i32_e32 v15, 12, v15
	v_mul_i32_i24_e32 v16, 0x1800, v15
	v_ashrrev_i32_e32 v17, 31, v16
	v_lshl_add_u64 v[30:31], v[16:17], 2, s[10:11]
	s_mov_b64 s[8:9], 0x1000
	v_lshl_add_u64 v[24:25], v[30:31], 0, s[8:9]
	s_andn2_b64 vcc, exec, s[16:17]
	v_lshl_add_u64 v[16:17], s[84:85], 0, v[50:51]
	s_cbranch_vccnz .LBB0_885
	v_lshl_add_u64 v[32:33], v[30:31], 0, v[0:1]
	v_lshl_add_u64 v[84:85], v[24:25], 0, v[0:1]
	s_waitcnt vmcnt(14)
	v_mov_b64_e32 v[76:77], v[122:123]
	v_mov_b64_e32 v[78:79], v[124:125]
	s_nop 0
	v_mov_b64_e32 v[84:85], v[138:139]
	v_mov_b64_e32 v[86:87], v[140:141]
	v_pk_add_f32 v[32:33], v[84:85], 1.0 op_sel_hi:[1,0]
	s_nop 0
	v_pk_fma_f32 v[2:3], v[2:3], v[32:33], v[76:77]
	v_pk_add_f32 v[32:33], v[86:87], 1.0 op_sel_hi:[1,0]
	v_cvt_pk_bf16_f32 v2, v2, v3
	v_pk_fma_f32 v[4:5], v[4:5], v[32:33], v[78:79]
	s_nop 0
	v_cvt_pk_bf16_f32 v3, v4, v5
	v_add_co_u32_e32 v4, vcc, 0x50cc000, v16
	s_nop 1
	v_addc_co_u32_e32 v5, vcc, 0, v17, vcc
	global_store_dwordx2 v[4:5], v[2:3], off offset:256

; DI void ln_rows(const Params& p, const float* g, const float* bb, int nrows, int mod_layer, int sh_chunk, bool write_act) {
;     ...
;         if (write_act) {
;           float4 sh = *(const float4*)(m + col);
;           float4 sc = *(const float4*)(m + 1024 + col);
;           uint2 o;
;           o.x = pack2(y.x * (1.f + sc.x) + sh.x, y.y * (1.f + sc.y) + sh.y);
;           o.y = pack2(y.z * (1.f + sc.z) + sh.z, y.w * (1.f + sc.w) + sh.w);
;           *(uint2*)(act + (size_t)row * AP + col) = o;
;         }
.LBB0_887:
	s_andn2_b64 vcc, exec, s[16:17]
	s_cbranch_vccnz .LBB0_889
	v_lshlrev_b32_e32 v72, 2, v38
	v_mov_b32_e32 v73, v1
	v_lshl_add_u64 v[32:33], v[30:31], 0, v[0:1]
	v_lshl_add_u64 v[76:77], v[24:25], 0, v[72:73]
	s_waitcnt vmcnt(13)
	v_mov_b64_e32 v[72:73], v[126:127]
	v_mov_b64_e32 v[74:75], v[128:129]
	s_nop 0
	v_mov_b64_e32 v[76:77], v[142:143]
	v_mov_b64_e32 v[78:79], v[144:145]
	v_pk_add_f32 v[32:33], v[76:77], 1.0 op_sel_hi:[1,0]
	s_nop 0
	v_pk_fma_f32 v[2:3], v[2:3], v[32:33], v[72:73]
	v_pk_add_f32 v[32:33], v[78:79], 1.0 op_sel_hi:[1,0]
	v_cvt_pk_bf16_f32 v2, v2, v3
	v_pk_fma_f32 v[4:5], v[4:5], v[32:33], v[74:75]
	s_nop 0
	v_cvt_pk_bf16_f32 v3, v4, v5
	v_add_co_u32_e32 v4, vcc, 0x50cc000, v16
	s_nop 1
	v_addc_co_u32_e32 v5, vcc, 0, v17, vcc
	global_store_dwordx2 v[4:5], v[2:3], off offset:768

; DI void ln_rows(const Params& p, const float* g, const float* bb, int nrows, int mod_layer, int sh_chunk, bool write_act) {
;     ...
;         if (write_act) {
;           float4 sh = *(const float4*)(m + col);
;           float4 sc = *(const float4*)(m + 1024 + col);
;           uint2 o;
;           o.x = pack2(y.x * (1.f + sc.x) + sh.x, y.y * (1.f + sc.y) + sh.y);
;           o.y = pack2(y.z * (1.f + sc.z) + sh.z, y.w * (1.f + sc.w) + sh.w);
;           *(uint2*)(act + (size_t)row * AP + col) = o;
;         }
.LBB0_891:
	s_andn2_b64 vcc, exec, s[16:17]
	s_cbranch_vccnz .LBB0_893
	v_lshlrev_b32_e32 v68, 2, v40
	v_mov_b32_e32 v69, v1
	v_lshl_add_u64 v[32:33], v[30:31], 0, v[0:1]
	v_lshl_add_u64 v[72:73], v[24:25], 0, v[68:69]
	s_waitcnt vmcnt(12)
	v_mov_b64_e32 v[68:69], v[130:131]
	v_mov_b64_e32 v[70:71], v[132:133]
	s_nop 0
	v_mov_b64_e32 v[72:73], v[146:147]
	v_mov_b64_e32 v[74:75], v[148:149]
	v_pk_add_f32 v[32:33], v[72:73], 1.0 op_sel_hi:[1,0]
	s_nop 0
	v_pk_fma_f32 v[2:3], v[2:3], v[32:33], v[68:69]
	v_pk_add_f32 v[32:33], v[74:75], 1.0 op_sel_hi:[1,0]
	v_cvt_pk_bf16_f32 v2, v2, v3
	v_pk_fma_f32 v[4:5], v[4:5], v[32:33], v[70:71]
	s_nop 0
	v_cvt_pk_bf16_f32 v3, v4, v5
	v_add_co_u32_e32 v4, vcc, 0x50cc000, v16
	s_nop 1
	v_addc_co_u32_e32 v5, vcc, 0, v17, vcc
	global_store_dwordx2 v[4:5], v[2:3], off offset:1280

; DI void ln_rows(const Params& p, const float* g, const float* bb, int nrows, int mod_layer, int sh_chunk, bool write_act) {
;     ...
;         if (write_act) {
;           float4 sh = *(const float4*)(m + col);
;           float4 sc = *(const float4*)(m + 1024 + col);
;           uint2 o;
;           o.x = pack2(y.x * (1.f + sc.x) + sh.x, y.y * (1.f + sc.y) + sh.y);
;           o.y = pack2(y.z * (1.f + sc.z) + sh.z, y.w * (1.f + sc.w) + sh.w);
;           *(uint2*)(act + (size_t)row * AP + col) = o;
;         }
.LBB0_897:
	v_lshlrev_b32_e32 v20, 2, v42
	v_mov_b32_e32 v21, v1
	v_lshl_add_u64 v[18:19], v[30:31], 0, v[0:1]
	v_lshl_add_u64 v[22:23], v[24:25], 0, v[20:21]
	s_waitcnt vmcnt(11)
	v_mov_b64_e32 v[18:19], v[134:135]
	v_mov_b64_e32 v[20:21], v[136:137]
	s_nop 0
	v_mov_b64_e32 v[22:23], v[150:151]
	v_mov_b64_e32 v[24:25], v[152:153]
	v_pk_add_f32 v[22:23], v[22:23], 1.0 op_sel_hi:[1,0]
	s_nop 0
	v_pk_fma_f32 v[2:3], v[2:3], v[22:23], v[18:19]
	v_pk_add_f32 v[18:19], v[24:25], 1.0 op_sel_hi:[1,0]
	v_cvt_pk_bf16_f32 v2, v2, v3
	v_pk_fma_f32 v[4:5], v[4:5], v[18:19], v[20:21]
	s_nop 0
	v_cvt_pk_bf16_f32 v3, v4, v5
	v_add_co_u32_e32 v4, vcc, 0x50cc000, v16
	s_nop 1
	v_addc_co_u32_e32 v5, vcc, 0, v17, vcc
	global_store_dwordx2 v[4:5], v[2:3], off offset:1792
	s_and_saveexec_b64 s[16:17], s[2:3]
	s_cbranch_execz .LBB0_870

; DI void ln_rows(const Params& p, const float* g, const float* bb, int nrows, int mod_layer, int sh_chunk, bool write_act) {
;     ...
;     for (int rr = 0; rr < 2; ++rr) {
;       if (rr == 1 && !has1) break;
;       const int row = rr ? row1 : row0;
;       const float rstd = rr ? rb : ra;
;       float* dst = xrow(p, row);
;       if (write_act && lane == 0) ((float2*)(p.ws + O_ST))[row] = make_float2(rr ? mb : ma, rstd);
;       const float* m = (const float*)(p.ws + O_MOD) + (size_t)mod_layer * 17 * 6144 + rowb(row) * 6144 + sh_chunk * 1024;
; #pragma unroll
;       for (int i = 0; i < 4; ++i) {
;         int col = (i * 64 + lane) * 4;
;         float4 v = rr ? vb[i] : va[i];
;         float4 gg = *(const float4*)(g + col);
;         float4 bv = *(const float4*)(bb + col);
;         float4 y;
;         y.x = v.x * rstd * gg.x + bv.x; y.y = v.y * rstd * gg.y + bv.y;
;         y.z = v.z * rstd * gg.z + bv.z; y.w = v.w * rstd * gg.w + bv.w;
;         if (!write_act) *(float4*)(dst + col) = y;
;         if (write_act) {
;           float4 sh = *(const float4*)(m + col);
;           float4 sc = *(const float4*)(m + 1024 + col);
;           uint2 o;
;           o.x = pack2(y.x * (1.f + sc.x) + sh.x, y.y * (1.f + sc.y) + sh.y);
;           o.y = pack2(y.z * (1.f + sc.z) + sh.z, y.w * (1.f + sc.w) + sh.w);
;           *(uint2*)(act + (size_t)row * AP + col) = o;
;         }
.LBB0_900:
	s_or_b64 exec, exec, s[2:3]
	s_waitcnt vmcnt(10)
	v_mov_b64_e32 v[2:3], v[90:91]
	v_mov_b64_e32 v[4:5], v[92:93]
	v_mov_b64_e32 v[18:19], v[106:107]
	v_mov_b64_e32 v[20:21], v[108:109]
	v_pk_mul_f32 v[14:15], v[64:65], v[16:17] op_sel_hi:[1,0]
	v_pk_mul_f32 v[22:23], v[62:63], v[16:17] op_sel_hi:[1,0]
	s_and_b64 vcc, exec, s[4:5]
	s_mov_b64 s[2:3], -1
	v_pk_fma_f32 v[2:3], v[14:15], v[2:3], v[18:19]
	v_pk_fma_f32 v[4:5], v[22:23], v[4:5], v[20:21]
	s_cbranch_vccnz .LBB0_902
	v_lshl_add_u64 v[14:15], v[58:59], 0, v[0:1]
	s_mov_b64 s[2:3], 0
	global_store_dwordx4 v[14:15], v[2:5], off
.LBB0_902:
	v_min_i32_e32 v14, 0x10000, v83
	v_ashrrev_i32_e32 v14, 12, v14
	v_mul_i32_i24_e32 v14, 0x1800, v14
	v_ashrrev_i32_e32 v15, 31, v14
	v_lshl_add_u64 v[20:21], v[14:15], 2, s[10:11]
	s_mov_b64 s[6:7], 0x1000
	v_lshl_add_u64 v[18:19], v[20:21], 0, s[6:7]
	s_andn2_b64 vcc, exec, s[2:3]
	v_lshl_add_u64 v[14:15], s[84:85], 0, v[56:57]
	s_cbranch_vccnz .LBB0_904
	v_lshl_add_u64 v[22:23], v[20:21], 0, v[0:1]
	v_lshl_add_u64 v[30:31], v[18:19], 0, v[0:1]
	s_waitcnt vmcnt(10)
	v_mov_b64_e32 v[22:23], v[170:171]
	v_mov_b64_e32 v[24:25], v[172:173]
	s_nop 0
	v_mov_b64_e32 v[30:31], v[174:175]
	v_mov_b64_e32 v[32:33], v[176:177]
	v_pk_add_f32 v[30:31], v[30:31], 1.0 op_sel_hi:[1,0]
	s_nop 0
	v_pk_fma_f32 v[2:3], v[2:3], v[30:31], v[22:23]
	v_pk_add_f32 v[22:23], v[32:33], 1.0 op_sel_hi:[1,0]
	v_cvt_pk_bf16_f32 v2, v2, v3
	v_pk_fma_f32 v[4:5], v[4:5], v[22:23], v[24:25]
	s_nop 0
	v_cvt_pk_bf16_f32 v3, v4, v5
	v_add_co_u32_e32 v4, vcc, 0x50cc000, v14
	s_nop 1
	v_addc_co_u32_e32 v5, vcc, 0, v15, vcc
	global_store_dwordx2 v[4:5], v[2:3], off offset:256
.LBB0_904:
	s_waitcnt vmcnt(9)
	v_mov_b64_e32 v[2:3], v[94:95]
	v_mov_b64_e32 v[4:5], v[96:97]
	s_nop 0
	v_mov_b64_e32 v[22:23], v[110:111]
	v_mov_b64_e32 v[24:25], v[112:113]
	v_mov_b32_e32 v17, v16
	v_pk_mul_f32 v[26:27], v[26:27], v[16:17]
	v_pk_mul_f32 v[28:29], v[28:29], v[16:17]
	s_and_b64 vcc, exec, s[4:5]
	s_mov_b64 s[2:3], -1
	v_pk_fma_f32 v[2:3], v[26:27], v[2:3], v[22:23]
	v_pk_fma_f32 v[4:5], v[28:29], v[4:5], v[24:25]
	s_cbranch_vccnz .LBB0_906
	v_lshl_add_u64 v[22:23], v[58:59], 0, v[0:1]
	s_mov_b64 s[2:3], 0
	global_store_dwordx4 v[22:23], v[2:5], off offset:1024
.LBB0_906:
	s_andn2_b64 vcc, exec, s[2:3]
	s_cbranch_vccnz .LBB0_908
	v_lshlrev_b32_e32 v24, 2, v38
	v_mov_b32_e32 v25, v1
	v_lshl_add_u64 v[22:23], v[20:21], 0, v[0:1]
	v_lshl_add_u64 v[26:27], v[18:19], 0, v[24:25]
	s_waitcnt vmcnt(9)
	v_mov_b64_e32 v[22:23], v[178:179]
	v_mov_b64_e32 v[24:25], v[180:181]
	s_nop 0
	v_mov_b64_e32 v[26:27], v[186:187]
	v_mov_b64_e32 v[28:29], v[188:189]
	v_pk_add_f32 v[26:27], v[26:27], 1.0 op_sel_hi:[1,0]
	s_nop 0
	v_pk_fma_f32 v[2:3], v[2:3], v[26:27], v[22:23]
	v_pk_add_f32 v[22:23], v[28:29], 1.0 op_sel_hi:[1,0]
	v_cvt_pk_bf16_f32 v2, v2, v3
	v_pk_fma_f32 v[4:5], v[4:5], v[22:23], v[24:25]
	s_nop 0
	v_cvt_pk_bf16_f32 v3, v4, v5
	v_add_co_u32_e32 v4, vcc, 0x50cc000, v14
	s_nop 1
	v_addc_co_u32_e32 v5, vcc, 0, v15, vcc
	global_store_dwordx2 v[4:5], v[2:3], off offset:768
.LBB0_908:
	s_waitcnt vmcnt(8)
	v_mov_b64_e32 v[2:3], v[98:99]
	v_mov_b64_e32 v[4:5], v[100:101]
	s_nop 0
	v_mov_b64_e32 v[22:23], v[114:115]
	v_mov_b64_e32 v[24:25], v[116:117]
	v_pk_mul_f32 v[12:13], v[12:13], v[16:17]
	v_pk_mul_f32 v[10:11], v[10:11], v[16:17]
	s_and_b64 vcc, exec, s[4:5]
	s_mov_b64 s[2:3], -1
	v_pk_fma_f32 v[2:3], v[12:13], v[2:3], v[22:23]
	v_pk_fma_f32 v[4:5], v[10:11], v[4:5], v[24:25]
	s_cbranch_vccnz .LBB0_910
	v_lshl_add_u64 v[10:11], v[58:59], 0, v[0:1]
	s_mov_b64 s[2:3], 0
	global_store_dwordx4 v[10:11], v[2:5], off offset:2048
.LBB0_910:
	s_andn2_b64 vcc, exec, s[2:3]
	s_cbranch_vccnz .LBB0_912
	v_lshlrev_b32_e32 v12, 2, v40
	v_mov_b32_e32 v13, v1
	v_lshl_add_u64 v[10:11], v[20:21], 0, v[0:1]
	v_lshl_add_u64 v[22:23], v[18:19], 0, v[12:13]
	s_waitcnt vmcnt(8)
	v_mov_b64_e32 v[10:11], v[190:191]
	v_mov_b64_e32 v[12:13], v[192:193]
	s_nop 0
	v_mov_b64_e32 v[22:23], v[194:195]
	v_mov_b64_e32 v[24:25], v[196:197]
	v_pk_add_f32 v[22:23], v[22:23], 1.0 op_sel_hi:[1,0]
	s_nop 0
	v_pk_fma_f32 v[2:3], v[2:3], v[22:23], v[10:11]
	v_pk_add_f32 v[10:11], v[24:25], 1.0 op_sel_hi:[1,0]
	v_cvt_pk_bf16_f32 v2, v2, v3
	v_pk_fma_f32 v[4:5], v[4:5], v[10:11], v[12:13]
	s_nop 0
	v_cvt_pk_bf16_f32 v3, v4, v5
	v_add_co_u32_e32 v4, vcc, 0x50cc000, v14
	s_nop 1
	v_addc_co_u32_e32 v5, vcc, 0, v15, vcc
	global_store_dwordx2 v[4:5], v[2:3], off offset:1280
.LBB0_912:
	s_waitcnt vmcnt(7)
	v_mov_b64_e32 v[2:3], v[102:103]
	v_mov_b64_e32 v[4:5], v[104:105]
	s_nop 0
	v_mov_b64_e32 v[10:11], v[118:119]
	v_mov_b64_e32 v[12:13], v[120:121]
	v_pk_mul_f32 v[8:9], v[8:9], v[16:17]
	v_pk_mul_f32 v[6:7], v[6:7], v[16:17]
	s_and_b64 vcc, exec, s[4:5]
	s_mov_b64 s[2:3], -1
	v_pk_fma_f32 v[2:3], v[8:9], v[2:3], v[10:11]
	v_pk_fma_f32 v[4:5], v[6:7], v[4:5], v[12:13]
	s_cbranch_vccnz .LBB0_914
	v_lshl_add_u64 v[6:7], v[58:59], 0, v[0:1]
	s_mov_b64 s[2:3], 0
	global_store_dwordx4 v[6:7], v[2:5], off offset:3072
.LBB0_914:
	s_andn2_b64 vcc, exec, s[2:3]
	s_cbranch_vccnz .LBB0_870
	v_lshl_add_u64 v[6:7], v[20:21], 0, v[0:1]
	v_lshlrev_b32_e32 v0, 2, v42
	v_lshl_add_u64 v[10:11], v[18:19], 0, v[0:1]
	s_waitcnt vmcnt(7)
	v_mov_b64_e32 v[6:7], v[198:199]
	v_mov_b64_e32 v[8:9], v[200:201]
	s_nop 0
	v_mov_b64_e32 v[10:11], v[202:203]
	v_mov_b64_e32 v[12:13], v[204:205]
	v_pk_add_f32 v[10:11], v[10:11], 1.0 op_sel_hi:[1,0]
	s_nop 0
	v_pk_fma_f32 v[2:3], v[2:3], v[10:11], v[6:7]
	v_pk_add_f32 v[6:7], v[12:13], 1.0 op_sel_hi:[1,0]
	v_cvt_pk_bf16_f32 v2, v2, v3
	v_pk_fma_f32 v[4:5], v[4:5], v[6:7], v[8:9]
	s_nop 0
	v_cvt_pk_bf16_f32 v3, v4, v5
	v_add_co_u32_e32 v4, vcc, 0x50cc000, v14
	s_nop 1
	v_addc_co_u32_e32 v5, vcc, 0, v15, vcc
	global_store_dwordx2 v[4:5], v[2:3], off offset:1792
	s_branch .LBB0_870
